# G1 K-loop: next K-step LDS fragment reads interleaved between MFMAs (was burst prefetch)
# speedup vs baseline: 1.0353x; 1.0017x over previous
.LBB0_1685:
	s_or_b64 exec, exec, s[6:7]
	s_add_i32 s6, s13, 0
	v_add_u32_e32 v120, s6, v109
	v_add_u32_e32 v119, s6, v110
	v_add_u32_e32 v121, v120, v112
	v_add_u32_e32 v166, v119, v112
	ds_read_b128 v[122:125], v121
	ds_read_b128 v[130:133], v121 offset:4096
	ds_read_b128 v[134:137], v121 offset:8192
	ds_read_b128 v[138:141], v121 offset:12288
	ds_read_b128 v[142:145], v166 offset:32768
	v_add_u32_e32 v121, v120, v111
	v_add_u32_e32 v166, v119, v111
	s_setprio 1
	s_waitcnt lgkmcnt(0)
	v_mfma_f32_32x32x16_bf16 v[48:63], v[122:125], v[142:145], v[48:63]
	ds_read_b128 v[146:149], v121
	ds_read_b128 v[150:153], v121 offset:4096
	v_mfma_f32_32x32x16_bf16 v[32:47], v[130:133], v[142:145], v[32:47]
	ds_read_b128 v[154:157], v121 offset:8192
	v_mfma_f32_32x32x16_bf16 v[16:31], v[134:137], v[142:145], v[16:31]
	ds_read_b128 v[158:161], v121 offset:12288
	v_mfma_f32_32x32x16_bf16 v[0:15], v[138:141], v[142:145], v[0:15]
	ds_read_b128 v[162:165], v166 offset:32768
	s_setprio 0
	v_add_u32_e32 v121, v120, v100
	v_add_u32_e32 v166, v119, v100
	s_setprio 1
	s_waitcnt lgkmcnt(0)
	v_mfma_f32_32x32x16_bf16 v[48:63], v[146:149], v[162:165], v[48:63]
	ds_read_b128 v[122:125], v121
	ds_read_b128 v[130:133], v121 offset:4096
	v_mfma_f32_32x32x16_bf16 v[32:47], v[150:153], v[162:165], v[32:47]
	ds_read_b128 v[134:137], v121 offset:8192
	v_mfma_f32_32x32x16_bf16 v[16:31], v[154:157], v[162:165], v[16:31]
	ds_read_b128 v[138:141], v121 offset:12288
	v_mfma_f32_32x32x16_bf16 v[0:15], v[158:161], v[162:165], v[0:15]
	ds_read_b128 v[142:145], v166 offset:32768
	s_setprio 0
	s_and_saveexec_b64 s[6:7], vcc
	s_cbranch_execz .LBB0_1687
	s_xor_b32 s13, s13, 0x10000
	s_add_i32 s13, s13, 0
	v_add_u32_e32 v121, s13, v106
	v_add_u32_e32 v148, s13, v105
	v_readfirstlane_b32 s14, v121
	v_lshl_add_u64 v[146:147], v[76:77], 0, s[4:5]
	s_mov_b32 m0, s14
	v_readfirstlane_b32 s14, v148
	v_add_u32_e32 v149, s13, v104
	global_load_lds_dwordx4 v[146:147], off
	v_lshl_add_u64 v[146:147], v[78:79], 0, s[4:5]
	s_mov_b32 m0, s14
	v_readfirstlane_b32 s14, v149
	v_add_u32_e32 v149, s13, v103
	global_load_lds_dwordx4 v[146:147], off
	v_lshl_add_u64 v[146:147], v[80:81], 0, s[4:5]
	s_mov_b32 m0, s14
	v_readfirstlane_b32 s13, v149
	v_add_u32_e32 v121, 0x8000, v121
	global_load_lds_dwordx4 v[146:147], off
	v_lshl_add_u64 v[146:147], v[82:83], 0, s[4:5]
	s_mov_b32 m0, s13
	v_readfirstlane_b32 s13, v121
	v_add_u32_e32 v121, 0x8000, v148
	global_load_lds_dwordx4 v[146:147], off
	v_lshl_add_u64 v[146:147], v[84:85], 0, s[4:5]
	s_mov_b32 m0, s13
	v_readfirstlane_b32 s13, v121
	global_load_lds_dwordx4 v[146:147], off
	v_lshl_add_u64 v[146:147], v[86:87], 0, s[4:5]
	s_mov_b32 m0, s13
	s_nop 0
	global_load_lds_dwordx4 v[146:147], off
.LBB0_1687:
	s_or_b64 exec, exec, s[6:7]
	v_add_u32_e32 v121, v120, v99
	v_add_u32_e32 v166, v119, v99
	s_setprio 1
	s_waitcnt lgkmcnt(0)
	v_mfma_f32_32x32x16_bf16 v[48:63], v[122:125], v[142:145], v[48:63]
	ds_read_b128 v[146:149], v121
	ds_read_b128 v[150:153], v121 offset:4096
	v_mfma_f32_32x32x16_bf16 v[32:47], v[130:133], v[142:145], v[32:47]
	ds_read_b128 v[154:157], v121 offset:8192
	v_mfma_f32_32x32x16_bf16 v[16:31], v[134:137], v[142:145], v[16:31]
	ds_read_b128 v[158:161], v121 offset:12288
	v_mfma_f32_32x32x16_bf16 v[0:15], v[138:141], v[142:145], v[0:15]
	ds_read_b128 v[162:165], v166 offset:32768
	s_setprio 0
	s_setprio 1
	s_waitcnt lgkmcnt(0)
	v_mfma_f32_32x32x16_bf16 v[48:63], v[146:149], v[162:165], v[48:63]
	v_mfma_f32_32x32x16_bf16 v[32:47], v[150:153], v[162:165], v[32:47]
	v_mfma_f32_32x32x16_bf16 v[16:31], v[154:157], v[162:165], v[16:31]
	v_mfma_f32_32x32x16_bf16 v[0:15], v[158:161], v[162:165], v[0:15]
	s_setprio 0
	s_xor_b32 s6, s9, 1
	s_waitcnt vmcnt(0)
	s_add_u32 s4, s4, 0x80
	s_addc_u32 s5, s5, 0
	s_cmpk_lg_i32 s4, 0x780
	s_waitcnt vmcnt(0)
	s_barrier
	s_cbranch_scc1 .LBB0_1683
	v_add_u32_e32 v70, s8, v117
	s_movk_i32 s4, 0x59
	v_cmp_lt_i32_e32 vcc, s4, v70
	s_mov_b32 s4, 0x2aaaaaab
	s_nop 0
	v_cndmask_b32_e32 v64, v70, v117, vcc
	v_mul_hi_i32 v65, v64, s4
	v_lshrrev_b32_e32 v66, 31, v65
	v_add_u32_e32 v68, v65, v66
	v_mul_lo_u32 v65, v68, 6
	v_sub_u32_e32 v64, v64, v65
	v_add_lshl_u32 v71, v64, v88, 8
	v_lshlrev_b32_e32 v64, 4, v118
	v_and_b32_e32 v128, 0x70, v64
	s_xor_b64 s[4:5], s[0:1], -1
	v_lshl_add_u64 v[66:67], s[42:43], 0, v[128:129]
	v_lshl_add_u64 v[64:65], s[44:45], 0, v[128:129]
	v_lshlrev_b32_e32 v72, 7, v68
	s_nor_b64 s[4:5], s[4:5], vcc
	s_and_saveexec_b64 s[14:15], s[4:5]
	s_xor_b64 s[4:5], exec, s[14:15]
	s_cbranch_execz .LBB0_1690
	s_lshl_b32 s7, s6, 16
	s_xor_b32 s13, s7, 0x10000
	v_add_u32_e32 v68, v71, v114
	s_add_i32 s13, s13, 0
	v_ashrrev_i32_e32 v69, 31, v68
	v_add_u32_e32 v73, s13, v106
	v_lshlrev_b64 v[68:69], 11, v[68:69]
	v_readfirstlane_b32 s14, v73
	v_add_u32_e32 v74, v113, v71
	v_lshl_add_u64 v[68:69], v[66:67], 0, v[68:69]
	s_mov_b32 m0, s14
	v_add_u32_e32 v80, s13, v105
	v_ashrrev_i32_e32 v75, 31, v74
	v_add_u32_e32 v76, v116, v71
	global_load_lds_dwordx4 v[68:69], off
	v_readfirstlane_b32 s14, v80
	v_add_u32_e32 v68, s13, v104
	v_lshlrev_b64 v[74:75], 11, v[74:75]
	v_ashrrev_i32_e32 v77, 31, v76
	v_add_u32_e32 v78, v115, v71
	s_mov_b32 m0, s14
	v_readfirstlane_b32 s14, v68
	v_add_u32_e32 v68, s13, v103
	v_lshlrev_b64 v[76:77], 11, v[76:77]
	v_ashrrev_i32_e32 v79, 31, v78
	v_lshl_add_u64 v[74:75], v[66:67], 0, v[74:75]
	v_readfirstlane_b32 s13, v68
	v_add_u32_e32 v68, v72, v114
	v_lshlrev_b64 v[78:79], 11, v[78:79]
	v_lshl_add_u64 v[76:77], v[66:67], 0, v[76:77]
	global_load_lds_dwordx4 v[74:75], off
	s_mov_b32 m0, s14
	v_ashrrev_i32_e32 v69, 31, v68
	v_add_u32_e32 v73, 0x8000, v73
	v_lshl_add_u64 v[78:79], v[66:67], 0, v[78:79]
	global_load_lds_dwordx4 v[76:77], off
	s_mov_b32 m0, s13
	v_lshlrev_b64 v[68:69], 11, v[68:69]
	v_readfirstlane_b32 s13, v73
	global_load_lds_dwordx4 v[78:79], off
	v_lshl_add_u64 v[68:69], v[64:65], 0, v[68:69]
	s_mov_b32 m0, s13
	v_add_u32_e32 v73, 0x8000, v80
	global_load_lds_dwordx4 v[68:69], off
	v_add_u32_e32 v68, v113, v72
	v_ashrrev_i32_e32 v69, 31, v68
	v_lshlrev_b64 v[68:69], 11, v[68:69]
	v_readfirstlane_b32 s13, v73
	v_lshl_add_u64 v[68:69], v[64:65], 0, v[68:69]
	s_mov_b32 m0, s13
	s_nop 0
	global_load_lds_dwordx4 v[68:69], off
